# prologue hb=bf16(x) loop software-pipelined 4 iterations per trip (next loads issued before current stores)
# speedup vs baseline: 1.0031x; 1.0021x over previous
; __device__ __forceinline__ u32x4 pack8(f32x4 a, f32x4 b) { u32x4 w; w.x = cvt_pk_bf16(a[0], a[1]); w.y = cvt_pk_bf16(a[2], a[3]); w.z = cvt_pk_bf16(b[0], b[1]); w.w = cvt_pk_bf16(b[2], b[3]); return w; }
; __global__ void __launch_bounds__(512, 2) hybrid_fwd(Args args) {
;     ...
;             for (int idx = gt; idx < M * 256; idx += NGT) { const size_t off = (size_t)idx * 8; *(u32x4*)(HB + off) = pack8(*(const f32x4*)(x_in + off), *(const f32x4*)(x_in + off + 4)); }
.LBB0_719:
	s_or_b64 exec, exec, s[14:15]
	s_mov_b32 s4, 0x400000
	v_cmp_gt_i32_e32 vcc, s4, v0
	s_and_saveexec_b64 s[4:5], vcc
	s_cbranch_execz .LBB0_722
	v_readlane_b32 s6, v255, 32
	v_lshlrev_b64 v[2:3], 5, v[0:1]
	v_readlane_b32 s7, v255, 33
	s_ashr_i32 s13, s12, 31
	v_lshl_add_u64 v[4:5], v[0:1], 4, s[8:9]
	v_lshl_add_u64 v[2:3], s[6:7], 0, v[2:3]
	v_lshl_add_u64 v[2:3], v[2:3], 0, 16
	s_lshl_b64 s[6:7], s[12:13], 5
	s_lshl_b64 s[8:9], s[12:13], 4
	s_mov_b64 s[10:11], 0
	v_readfirstlane_b32 s14, v0
	s_mul_i32 s15, s12, 3
	s_mov_b32 s16, 0x3fffff
	s_add_i32 s14, s14, 63
	s_add_i32 s14, s14, s15
	s_lshl_b32 s15, s12, 2
	s_cmp_gt_i32 s14, s16
	s_cbranch_scc1 .LBB0_721
	global_load_dwordx4 v[14:17], v[2:3], off offset:-16
	global_load_dwordx4 v[18:21], v[2:3], off
	v_lshl_add_u64 v[2:3], v[2:3], 0, s[6:7]
	global_load_dwordx4 v[22:25], v[2:3], off offset:-16
	global_load_dwordx4 v[26:29], v[2:3], off
	v_lshl_add_u64 v[2:3], v[2:3], 0, s[6:7]
	global_load_dwordx4 v[30:33], v[2:3], off offset:-16
	global_load_dwordx4 v[34:37], v[2:3], off
	v_lshl_add_u64 v[2:3], v[2:3], 0, s[6:7]
	global_load_dwordx4 v[38:41], v[2:3], off offset:-16
	global_load_dwordx4 v[42:45], v[2:3], off
	v_lshl_add_u64 v[2:3], v[2:3], 0, s[6:7]
	v_add_u32_e32 v0, s15, v0
	s_waitcnt vmcnt(0)
	s_branch .Lmy_hb_cvt

; __device__ __forceinline__ u32x4 pack8(f32x4 a, f32x4 b) { u32x4 w; w.x = cvt_pk_bf16(a[0], a[1]); w.y = cvt_pk_bf16(a[2], a[3]); w.z = cvt_pk_bf16(b[0], b[1]); w.w = cvt_pk_bf16(b[2], b[3]); return w; }
; __global__ void __launch_bounds__(512, 2) hybrid_fwd(Args args) {
;     ...
;             for (int idx = gt; idx < M * 256; idx += NGT) { const size_t off = (size_t)idx * 8; *(u32x4*)(HB + off) = pack8(*(const f32x4*)(x_in + off), *(const f32x4*)(x_in + off + 4)); }
.Lmy_hb_cvt:
	v_cvt_pk_bf16_f32 v46, v14, v15
	v_cvt_pk_bf16_f32 v47, v16, v17
	v_cvt_pk_bf16_f32 v48, v18, v19
	v_cvt_pk_bf16_f32 v49, v20, v21
	v_cvt_pk_bf16_f32 v50, v22, v23
	v_cvt_pk_bf16_f32 v51, v24, v25
	v_cvt_pk_bf16_f32 v52, v26, v27
	v_cvt_pk_bf16_f32 v53, v28, v29
	v_cvt_pk_bf16_f32 v54, v30, v31
	v_cvt_pk_bf16_f32 v55, v32, v33
	v_cvt_pk_bf16_f32 v56, v34, v35
	v_cvt_pk_bf16_f32 v57, v36, v37
	v_cvt_pk_bf16_f32 v58, v38, v39
	v_cvt_pk_bf16_f32 v59, v40, v41
	v_cvt_pk_bf16_f32 v60, v42, v43
	v_cvt_pk_bf16_f32 v61, v44, v45
	s_add_i32 s14, s14, s15
	s_cmp_gt_i32 s14, s16
	s_cbranch_scc1 .Lmy_hb_last
	global_load_dwordx4 v[14:17], v[2:3], off offset:-16
	global_load_dwordx4 v[18:21], v[2:3], off
	v_lshl_add_u64 v[2:3], v[2:3], 0, s[6:7]
	global_load_dwordx4 v[22:25], v[2:3], off offset:-16
	global_load_dwordx4 v[26:29], v[2:3], off
	v_lshl_add_u64 v[2:3], v[2:3], 0, s[6:7]
	global_load_dwordx4 v[30:33], v[2:3], off offset:-16
	global_load_dwordx4 v[34:37], v[2:3], off
	v_lshl_add_u64 v[2:3], v[2:3], 0, s[6:7]
	global_load_dwordx4 v[38:41], v[2:3], off offset:-16
	global_load_dwordx4 v[42:45], v[2:3], off
	v_lshl_add_u64 v[2:3], v[2:3], 0, s[6:7]
	v_add_u32_e32 v0, s15, v0
	global_store_dwordx4 v[4:5], v[46:49], off
	v_lshl_add_u64 v[4:5], v[4:5], 0, s[8:9]
	global_store_dwordx4 v[4:5], v[50:53], off
	v_lshl_add_u64 v[4:5], v[4:5], 0, s[8:9]
	global_store_dwordx4 v[4:5], v[54:57], off
	v_lshl_add_u64 v[4:5], v[4:5], 0, s[8:9]
	global_store_dwordx4 v[4:5], v[58:61], off
	v_lshl_add_u64 v[4:5], v[4:5], 0, s[8:9]
	s_branch .Lmy_hb_loop
.Lmy_hb_last:
	global_store_dwordx4 v[4:5], v[46:49], off
	v_lshl_add_u64 v[4:5], v[4:5], 0, s[8:9]
	global_store_dwordx4 v[4:5], v[50:53], off
	v_lshl_add_u64 v[4:5], v[4:5], 0, s[8:9]
	global_store_dwordx4 v[4:5], v[54:57], off
	v_lshl_add_u64 v[4:5], v[4:5], 0, s[8:9]
	global_store_dwordx4 v[4:5], v[58:61], off
	v_lshl_add_u64 v[4:5], v[4:5], 0, s[8:9]
	v_cmp_lt_i32_e32 vcc, s16, v0
	s_or_b64 s[10:11], vcc, s[10:11]
	s_andn2_b64 exec, exec, s[10:11]
	s_cbranch_execz .LBB0_722
